# baseline (speedup 1.0000x reference)
; __device__ __forceinline__ float bflo(unsigned w) { return __uint_as_float(w << 16); }
; __device__ __forceinline__ float bfhi(unsigned w) { return __uint_as_float(w & 0xffff0000u); }
; #define AISSUE(k0, soff) do { const char* kb_ = (const char*)Kn + (size_t)(k0) * 4096; const char* rb_ = (const char*)Kr + (size_t)(k0) * 1024; \
;     char* st_ = lds + (soff) + tid * 16; \
;     GLDS(kb_ + vkn0, st_ + KOFF); GLDS(kb_ + vkn1, st_ + KOFF + 8192); GLDS(rb_ + vkr, st_ + KOFF + KROPE_OFF); \
;     GLDS(kb_ + vv0, st_); GLDS(kb_ + vv1, st_ + 8192); } while (0)
; __device__ __forceinline__ void attn_body(const u16* __restrict__ Qb, const u16* __restrict__ Kn, const u16* __restrict__ Kr,
;                                           u16* __restrict__ Ob, char* lds, int tid, const float* __restrict__ gq_, const float* __restrict__ tab_, int qpos0, float negM) {
;   const int wid = tid >> 6, lane = tid & 63, r32 = lane & 31, hi = lane >> 5;
;   float* wsp = (float*)(lds + 3 * 40960) + wid * 64; float* li_l = wsp;
;   float l_reg = 0; f32x16 o[4] = {}; bf16x8 qr[12];
;   unsigned vkn0, vkn1, vkr, vv0, vv1;
;   { int sl = tid;        int row = sl >> 4, c = (sl & 15) ^ (row & 15);        vkn0 = (unsigned)(row * 4096 + c * 16);
;     sl = tid + 512;      row = sl >> 4;     c = (sl & 15) ^ (row & 15);        vkn1 = (unsigned)(row * 4096 + c * 16);
;     row = tid >> 3;      c = (tid & 7) ^ ((row >> 1) & 7);                     vkr  = (unsigned)(row * 1024 + c * 16);
; #pragma unroll
;     for (int i = 0; i < 2; ++i) { const int o = (tid + i * 512) * 16, sub = o >> 9, within = o & 511;
;       const int kk = (sub >> 2) * 8 + (within >> 6), cc = (sub & 3) * 32 + ((within & 63) >> 1);
;       const int k = (kk & ~0xC) | ((kk & 4) << 1) | ((kk & 8) >> 1);
;       const unsigned v = (unsigned)(k * 4096 + cc * 2 + 256);
;       if (i == 0) vv0 = v; else vv1 = v; } }
;   constexpr int STG = 40960, KOFF = 16384;
;     ...
;   AISSUE(0, 0);
;   {
;     const char* Qw = (const char*)Qb + (unsigned)(((wid * 32 + r32) * 1536 + hi * 8) * 2);
;     u32x4 qw[12];
; #pragma unroll
;     for (int d0 = 0; d0 < 12; ++d0) qw[d0] = *reinterpret_cast<const u32x4*>(Qw + d0 * 32);
;     float ss = 0.f;
; #pragma unroll
;     for (int d0 = 0; d0 < 12; ++d0)
; #pragma unroll
;       for (int e = 0; e < 4; ++e) { const float a = bflo(qw[d0][e]), b = bfhi(qw[d0][e]); ss += a * a + b * b; }
.LBB0_718:
	s_lshl_b32 s87, s3, 4
	s_lshl_b32 s0, s71, 10
	s_and_b32 s80, s0, 0x7e00000
	s_lshl_b32 s0, s71, 12
	v_mbcnt_lo_u32_b32 v96, -1, 0
	v_mbcnt_hi_u32_b32 v96, -1, v96
	s_and_b32 s79, s0, 0x1f800000
	v_or_b32_e32 v210, s3, v96
	s_lshl_b32 s0, s56, 8
	v_ashrrev_i32_e32 v20, 1, v210
	s_and_b32 s54, s0, 0x1f800
	s_mul_i32 s48, s56, 0xc0000
	v_bfi_b32 v66, s76, v20, v96
	s_mul_hi_u32 s49, s0, 0xc00
	s_add_u32 s50, s57, s48
	v_bfe_u32 v207, v96, 5, 1
	v_mul_lo_u32 v21, v66, s72
	s_addc_u32 s51, s58, s49
	v_lshl_or_b32 v67, v207, 4, v21
	s_barrier
	global_load_dwordx4 v[24:27], v67, s[50:51]
	v_lshlrev_b32_e32 v211, 4, v210
	v_bfe_u32 v23, v210, 2, 2
	v_lshrrev_b32_e32 v28, 1, v210
	v_and_or_b32 v23, v28, 8, v23
	v_lshlrev_b32_e32 v28, 1, v210
	v_and_b32_e32 v29, 48, v211
	v_and_or_b32 v38, v28, s73, v29
	v_bfe_i32 v28, v210, 4, 24
	v_and_b32_e32 v29, 0xffff0, v28
	v_lshrrev_b32_e32 v28, 1, v28
	v_and_b32_e32 v28, 4, v28
	v_or3_b32 v28, v29, v28, v23
	v_lshlrev_b32_e32 v36, 12, v28
	global_load_dwordx4 v[28:31], v67, s[50:51] offset:32
	global_load_dwordx4 v[42:45], v67, s[50:51] offset:64
	global_load_dwordx4 v[46:49], v67, s[50:51] offset:96
	v_add_u32_e32 v50, 0x2000, v211
	v_ashrrev_i32_e32 v33, 8, v50
	v_ashrrev_i32_e32 v16, 4, v210
	v_add_u32_e32 v18, 0x200, v210
	v_and_b32_e32 v34, 0xffff0, v33
	v_lshrrev_b32_e32 v33, 1, v33
	v_xor_b32_e32 v17, v16, v96
	v_ashrrev_i32_e32 v18, 4, v18
	v_and_b32_e32 v33, 4, v33
	v_lshlrev_b32_e32 v17, 4, v17
	v_xor_b32_e32 v19, v18, v96
	v_or3_b32 v23, v34, v33, v23
	v_lshlrev_b32_e32 v16, 12, v16
	v_lshlrev_b32_e32 v19, 4, v19
	v_lshlrev_b32_e32 v21, 7, v210
	v_or_b32_e32 v32, 0x100, v38
	v_lshlrev_b32_e32 v23, 12, v23
	v_and_or_b32 v176, v17, s74, v16
	v_lshlrev_b32_e32 v16, 12, v18
	v_bitop3_b32 v22, v211, v96, s3 bitop3:0x1e
	v_or_b32_e32 v80, v36, v32
	v_or_b32_e32 v81, v23, v32
	v_and_or_b32 v32, v19, s74, v16
	v_and_b32_e32 v16, 0xfffffc00, v21
	s_lshl_b32 s48, s54, 12
	v_and_or_b32 v34, v22, s75, v16
	v_add_u32_e32 v16, 0x4000, v211
	s_add_u32 s48, s61, s48
	v_readfirstlane_b32 s82, v16
	v_add_u32_e32 v16, 0x6000, v211
	s_addc_u32 s49, s62, 0
	s_lshl_b32 s54, s54, 10
	s_mov_b32 m0, s82
	v_readfirstlane_b32 s82, v16
	v_add_u32_e32 v16, 0x8000, v211
	s_add_u32 s54, s65, s54
	global_load_lds_dwordx4 v176, s[48:49]
	s_mov_b32 m0, s82
	v_readfirstlane_b32 s82, v16
	s_addc_u32 s55, s66, 0
	global_load_lds_dwordx4 v32, s[48:49]
	v_mov_b32_e32 v35, v177
	s_mov_b32 m0, s82
	v_or_b32_e32 v36, v38, v36
	v_mov_b32_e32 v37, v177
	v_lshl_add_u64 v[40:41], s[54:55], 0, v[34:35]
	global_load_lds_dwordx4 v34, s[54:55]
	v_lshl_add_u64 v[16:17], s[48:49], 0, v[36:37]
	v_readfirstlane_b32 s54, v211
	v_lshl_add_u64 v[16:17], v[16:17], 0, s[4:5]
	s_mov_b32 m0, s54
	v_or_b32_e32 v38, v38, v23
	v_mov_b32_e32 v39, v177
	global_load_lds_dwordx4 v[16:17], off
	v_lshl_add_u64 v[16:17], s[48:49], 0, v[38:39]
	v_readfirstlane_b32 s54, v50
	v_lshl_add_u64 v[16:17], v[16:17], 0, s[4:5]
	s_mov_b32 m0, s54
	v_and_b32_e32 v208, 0xffffffe0, v20
	global_load_lds_dwordx4 v[16:17], off
	global_load_dwordx4 v[50:53], v67, s[50:51] offset:128
	global_load_dwordx4 v[54:57], v67, s[50:51] offset:160
	global_load_dwordx4 v[58:61], v67, s[50:51] offset:192
	global_load_dwordx4 v[62:65], v67, s[50:51] offset:224
	s_nop 0
	global_load_dwordx4 v[16:19], v67, s[50:51] offset:256
	global_load_dwordx4 v[68:71], v67, s[50:51] offset:288
	global_load_dwordx4 v[20:23], v67, s[50:51] offset:320
	global_load_dwordx4 v[72:75], v67, s[50:51] offset:352
	s_waitcnt vmcnt(0)
	v_and_b32_e32 v133, 0xffff0000, v24
	v_and_b32_e32 v155, 0xffff0000, v25
	v_lshlrev_b32_e32 v132, 16, v24
	v_mul_f32_e32 v24, v133, v133
	v_lshlrev_b32_e32 v154, 16, v25
	v_mul_f32_e32 v25, v155, v155
	v_fmac_f32_e32 v24, v132, v132
	v_fmac_f32_e32 v25, v154, v154
	v_and_b32_e32 v163, 0xffff0000, v26
	v_add_f32_e32 v24, v24, v25
	v_lshlrev_b32_e32 v162, 16, v26
	v_mul_f32_e32 v25, v163, v163
	v_fmac_f32_e32 v25, v162, v162
	v_and_b32_e32 v165, 0xffff0000, v27
	v_add_f32_e32 v24, v25, v24
	v_lshlrev_b32_e32 v164, 16, v27
	v_mul_f32_e32 v25, v165, v165
	v_fmac_f32_e32 v25, v164, v164
	v_and_b32_e32 v167, 0xffff0000, v28
	v_add_f32_e32 v24, v25, v24
	v_lshlrev_b32_e32 v166, 16, v28
	v_mul_f32_e32 v25, v167, v167
	v_fmac_f32_e32 v25, v166, v166
	v_and_b32_e32 v169, 0xffff0000, v29
	v_add_f32_e32 v24, v25, v24
	v_lshlrev_b32_e32 v168, 16, v29
	v_mul_f32_e32 v25, v169, v169
	v_fmac_f32_e32 v25, v168, v168
	v_and_b32_e32 v125, 0xffff0000, v30
	v_add_f32_e32 v24, v25, v24
	v_lshlrev_b32_e32 v126, 16, v30
	v_mul_f32_e32 v25, v125, v125
	v_fmac_f32_e32 v25, v126, v126
	v_and_b32_e32 v127, 0xffff0000, v31
	v_add_f32_e32 v24, v25, v24
	v_lshlrev_b32_e32 v170, 16, v31
	v_mul_f32_e32 v25, v127, v127
	v_fmac_f32_e32 v25, v170, v170
	v_and_b32_e32 v172, 0xffff0000, v42
	v_add_f32_e32 v24, v25, v24
	v_lshlrev_b32_e32 v171, 16, v42
	v_mul_f32_e32 v25, v172, v172
	v_fmac_f32_e32 v25, v171, v171
	v_and_b32_e32 v174, 0xffff0000, v43
	v_add_f32_e32 v24, v25, v24
	v_lshlrev_b32_e32 v173, 16, v43
	v_mul_f32_e32 v25, v174, v174
	v_fmac_f32_e32 v25, v173, v173
	v_and_b32_e32 v178, 0xffff0000, v44
	v_add_f32_e32 v24, v25, v24
	v_lshlrev_b32_e32 v175, 16, v44
	v_mul_f32_e32 v25, v178, v178
	v_fmac_f32_e32 v25, v175, v175
	v_and_b32_e32 v117, 0xffff0000, v45
	v_add_f32_e32 v24, v25, v24
	v_lshlrev_b32_e32 v118, 16, v45
	v_mul_f32_e32 v25, v117, v117
	v_fmac_f32_e32 v25, v118, v118
	v_and_b32_e32 v119, 0xffff0000, v46
	v_add_f32_e32 v24, v25, v24
	v_lshlrev_b32_e32 v120, 16, v46
	v_mul_f32_e32 v25, v119, v119
	v_fmac_f32_e32 v25, v120, v120
	v_and_b32_e32 v121, 0xffff0000, v47
	v_add_f32_e32 v24, v25, v24
; __device__ __forceinline__ float bflo(unsigned w) { return __uint_as_float(w << 16); }
; __device__ __forceinline__ float bfhi(unsigned w) { return __uint_as_float(w & 0xffff0000u); }
; __device__ __forceinline__ void attn_body(const u16* __restrict__ Qb, const u16* __restrict__ Kn, const u16* __restrict__ Kr,
;                                           u16* __restrict__ Ob, char* lds, int tid, const float* __restrict__ gq_, const float* __restrict__ tab_, int qpos0, float negM) {
;     ...
;     for (int d0 = 0; d0 < 12; ++d0)
; #pragma unroll
;       for (int e = 0; e < 4; ++e) { const float a = bflo(qw[d0][e]), b = bfhi(qw[d0][e]); ss += a * a + b * b; }
;     { auto rr = __builtin_amdgcn_permlane32_swap(__float_as_uint(ss), __float_as_uint(ss), false, false);
;       ss = __uint_as_float(rr[0]) + __uint_as_float(rr[1]); }
;     const float rq = rsqrtf(ss * (1.f / 192.f) + EPS) * QSCALE;
;     const float* gq = gq_ + hi * 8;
; #pragma unroll
;     for (int d0 = 0; d0 < 8; ++d0) {
;       const f32x4 g0 = *reinterpret_cast<const f32x4*>(gq + d0 * 16), g1 = *reinterpret_cast<const f32x4*>(gq + d0 * 16 + 4);
;       const u32x4 w = qw[d0];
;       const u32x4 o = {cvtpk(bflo(w[0]) * rq * g0[0], bfhi(w[0]) * rq * g0[1]), cvtpk(bflo(w[1]) * rq * g0[2], bfhi(w[1]) * rq * g0[3]),
;                        cvtpk(bflo(w[2]) * rq * g1[0], bfhi(w[2]) * rq * g1[1]), cvtpk(bflo(w[3]) * rq * g1[2], bfhi(w[3]) * rq * g1[3])};
;       qr[d0] = *reinterpret_cast<const bf16x8*>(&o); }
	v_lshlrev_b32_e32 v122, 16, v47
	v_mul_f32_e32 v25, v121, v121
	v_fmac_f32_e32 v25, v122, v122
	v_and_b32_e32 v123, 0xffff0000, v48
	v_add_f32_e32 v24, v25, v24
	v_lshlrev_b32_e32 v124, 16, v48
	v_mul_f32_e32 v25, v123, v123
	v_fmac_f32_e32 v25, v124, v124
	v_and_b32_e32 v110, 0xffff0000, v49
	v_add_f32_e32 v24, v25, v24
	v_lshlrev_b32_e32 v111, 16, v49
	v_mul_f32_e32 v25, v110, v110
	v_fmac_f32_e32 v25, v111, v111
	v_and_b32_e32 v112, 0xffff0000, v50
	v_add_f32_e32 v24, v25, v24
	v_lshlrev_b32_e32 v113, 16, v50
	v_mul_f32_e32 v25, v112, v112
	v_fmac_f32_e32 v25, v113, v113
	v_and_b32_e32 v114, 0xffff0000, v51
	v_add_f32_e32 v24, v25, v24
	v_lshlrev_b32_e32 v115, 16, v51
	v_mul_f32_e32 v25, v114, v114
	v_fmac_f32_e32 v25, v115, v115
	v_and_b32_e32 v90, 0xffff0000, v52
	v_add_f32_e32 v24, v25, v24
	v_lshlrev_b32_e32 v116, 16, v52
	v_mul_f32_e32 v25, v90, v90
	v_fmac_f32_e32 v25, v116, v116
	v_and_b32_e32 v94, 0xffff0000, v53
	v_add_f32_e32 v24, v25, v24
	v_lshlrev_b32_e32 v98, 16, v53
	v_mul_f32_e32 v25, v94, v94
	v_fmac_f32_e32 v25, v98, v98
	v_and_b32_e32 v99, 0xffff0000, v54
	v_add_f32_e32 v24, v25, v24
	v_lshlrev_b32_e32 v103, 16, v54
	v_mul_f32_e32 v25, v99, v99
	v_fmac_f32_e32 v25, v103, v103
	v_and_b32_e32 v104, 0xffff0000, v55
	v_add_f32_e32 v24, v25, v24
	v_lshlrev_b32_e32 v106, 16, v55
	v_mul_f32_e32 v25, v104, v104
	v_fmac_f32_e32 v25, v106, v106
	v_and_b32_e32 v107, 0xffff0000, v56
	v_add_f32_e32 v24, v25, v24
	v_lshlrev_b32_e32 v108, 16, v56
	v_mul_f32_e32 v25, v107, v107
	v_fmac_f32_e32 v25, v108, v108
	v_and_b32_e32 v82, 0xffff0000, v57
	v_add_f32_e32 v24, v25, v24
	v_lshlrev_b32_e32 v109, 16, v57
	v_mul_f32_e32 v25, v82, v82
	v_fmac_f32_e32 v25, v109, v109
	v_and_b32_e32 v83, 0xffff0000, v58
	v_add_f32_e32 v24, v25, v24
	v_lshlrev_b32_e32 v84, 16, v58
	v_mul_f32_e32 v25, v83, v83
	v_fmac_f32_e32 v25, v84, v84
	v_and_b32_e32 v85, 0xffff0000, v59
	v_add_f32_e32 v24, v25, v24
	v_lshlrev_b32_e32 v86, 16, v59
	v_mul_f32_e32 v25, v85, v85
	v_fmac_f32_e32 v25, v86, v86
	v_and_b32_e32 v87, 0xffff0000, v60
	v_add_f32_e32 v24, v25, v24
	v_lshlrev_b32_e32 v88, 16, v60
	v_mul_f32_e32 v25, v87, v87
	v_fmac_f32_e32 v25, v88, v88
	v_and_b32_e32 v89, 0xffff0000, v61
	v_add_f32_e32 v24, v25, v24
	v_lshlrev_b32_e32 v91, 16, v61
	v_mul_f32_e32 v25, v89, v89
	v_fmac_f32_e32 v25, v91, v91
	v_and_b32_e32 v92, 0xffff0000, v62
	v_add_f32_e32 v24, v25, v24
	v_lshlrev_b32_e32 v95, 16, v62
	v_mul_f32_e32 v25, v92, v92
	v_fmac_f32_e32 v25, v95, v95
	v_and_b32_e32 v93, 0xffff0000, v63
	v_add_f32_e32 v24, v25, v24
	v_lshlrev_b32_e32 v100, 16, v63
	v_mul_f32_e32 v25, v93, v93
	v_fmac_f32_e32 v25, v100, v100
	v_and_b32_e32 v97, 0xffff0000, v64
	v_add_f32_e32 v24, v25, v24
	v_lshlrev_b32_e32 v101, 16, v64
	v_mul_f32_e32 v25, v97, v97
	v_fmac_f32_e32 v25, v101, v101
	v_and_b32_e32 v102, 0xffff0000, v65
	v_add_f32_e32 v24, v25, v24
	v_lshlrev_b32_e32 v105, 16, v65
	v_mul_f32_e32 v25, v102, v102
	v_fmac_f32_e32 v25, v105, v105
	v_and_b32_e32 v58, 32, v96
	v_add_u32_e32 v254, 0x1e800, v58
	v_add_f32_e32 v146, v25, v24
	ds_read_b128 v[24:27], v254 offset:16
	ds_read_b128 v[28:31], v254
	ds_read_b128 v[134:137], v254 offset:80
	ds_read_b128 v[138:141], v254 offset:64
	s_and_b32 s81, s0, 0x700
	v_add_u32_e32 v42, s81, v66
	v_ashrrev_i32_e32 v43, 31, v42
	v_lshlrev_b64 v[42:43], 7, v[42:43]
	v_lshl_add_u64 v[66:67], s[8:9], 0, v[42:43]
	v_and_b32_e32 v42, 0xffff0000, v75
	v_and_b32_e32 v46, 0xffff0000, v74
	v_lshlrev_b32_e32 v44, 16, v75
	v_lshlrev_b32_e32 v48, 16, v74
	v_mov_b32_e32 v52, v42
	v_mov_b32_e32 v53, v46
	v_mov_b32_e32 v50, v44
	v_mov_b32_e32 v51, v48
	v_pk_mul_f32 v[52:53], v[52:53], v[52:53]
	v_and_b32_e32 v54, 0xffff0000, v72
	v_pk_fma_f32 v[78:79], v[50:51], v[50:51], v[52:53]
	v_and_b32_e32 v50, 0xffff0000, v73
	v_lshlrev_b32_e32 v52, 16, v73
	v_lshlrev_b32_e32 v56, 16, v72
	v_mov_b32_e32 v62, v50
	v_mov_b32_e32 v63, v54
	v_mov_b32_e32 v60, v52
	v_mov_b32_e32 v61, v56
	v_pk_mul_f32 v[62:63], v[62:63], v[62:63]
	v_lshlrev_b32_e32 v53, 16, v69
	v_and_b32_e32 v51, 0xffff0000, v69
	v_lshlrev_b32_e32 v57, 16, v68
	v_and_b32_e32 v55, 0xffff0000, v68
	v_pk_fma_f32 v[68:69], v[60:61], v[60:61], v[62:63]
	v_and_b32_e32 v60, 0xffff0000, v23
	v_lshlrev_b32_e32 v64, 16, v22
	v_and_b32_e32 v22, 0xffff0000, v22
	v_lshlrev_b32_e32 v45, 16, v71
	v_and_b32_e32 v43, 0xffff0000, v71
	v_lshlrev_b32_e32 v49, 16, v70
	v_and_b32_e32 v47, 0xffff0000, v70
	v_lshlrev_b32_e32 v62, 16, v23
	v_mov_b32_e32 v70, v60
	v_mov_b32_e32 v71, v22
	v_lshlrev_b32_e32 v63, 16, v19
	v_and_b32_e32 v61, 0xffff0000, v19
	v_lshlrev_b32_e32 v65, 16, v18
	v_and_b32_e32 v23, 0xffff0000, v18
	v_mov_b32_e32 v18, v62
	v_mov_b32_e32 v19, v64
	v_pk_mul_f32 v[70:71], v[70:71], v[70:71]
	v_and_b32_e32 v75, 0xffff0000, v16
	v_and_b32_e32 v74, 0xffff0000, v20
	v_pk_fma_f32 v[128:129], v[18:19], v[18:19], v[70:71]
	v_lshlrev_b32_e32 v72, 16, v21
	v_and_b32_e32 v71, 0xffff0000, v17
	v_and_b32_e32 v70, 0xffff0000, v21
	v_lshlrev_b32_e32 v77, 16, v16
	v_lshlrev_b32_e32 v76, 16, v20
	v_pk_mul_f32 v[20:21], v[74:75], v[74:75]
	v_lshlrev_b32_e32 v73, 16, v17
	v_pk_mul_f32 v[18:19], v[70:71], v[70:71]
	v_pk_fma_f32 v[20:21], v[76:77], v[76:77], v[20:21]
	v_mul_f32_e32 v152, v65, v65
	v_pk_fma_f32 v[130:131], v[72:73], v[72:73], v[18:19]
	v_add_f32_e32 v21, v21, v146
	v_mul_f32_e32 v151, v63, v63
	v_fmac_f32_e32 v152, v23, v23
	v_add_f32_e32 v21, v131, v21
	v_mul_f32_e32 v150, v57, v57
	v_fmac_f32_e32 v151, v61, v61
	v_add_f32_e32 v21, v152, v21
	v_mul_f32_e32 v149, v53, v53
	v_fmac_f32_e32 v150, v55, v55
	v_add_f32_e32 v21, v151, v21
	v_mul_f32_e32 v148, v49, v49
	v_fmac_f32_e32 v149, v51, v51
; __device__ __forceinline__ float bflo(unsigned w) { return __uint_as_float(w << 16); }
; __device__ __forceinline__ float bfhi(unsigned w) { return __uint_as_float(w & 0xffff0000u); }
; __device__ __forceinline__ void attn_body(const u16* __restrict__ Qb, const u16* __restrict__ Kn, const u16* __restrict__ Kr,
;                                           u16* __restrict__ Ob, char* lds, int tid, const float* __restrict__ gq_, const float* __restrict__ tab_, int qpos0, float negM) {
;     ...
;     const float rq = rsqrtf(ss * (1.f / 192.f) + EPS) * QSCALE;
;     const float* gq = gq_ + hi * 8;
; #pragma unroll
;     for (int d0 = 0; d0 < 8; ++d0) {
;       const f32x4 g0 = *reinterpret_cast<const f32x4*>(gq + d0 * 16), g1 = *reinterpret_cast<const f32x4*>(gq + d0 * 16 + 4);
;       const u32x4 w = qw[d0];
;       const u32x4 o = {cvtpk(bflo(w[0]) * rq * g0[0], bfhi(w[0]) * rq * g0[1]), cvtpk(bflo(w[1]) * rq * g0[2], bfhi(w[1]) * rq * g0[3]),
;                        cvtpk(bflo(w[2]) * rq * g1[0], bfhi(w[2]) * rq * g1[1]), cvtpk(bflo(w[3]) * rq * g1[2], bfhi(w[3]) * rq * g1[3])};
;       qr[d0] = *reinterpret_cast<const bf16x8*>(&o); }
;     const float* tcp = tab_ + (size_t)(qpos0 + wid * 32 + r32) * 32 + hi * 8; const float* tsp = tcp + SEQ * 32;
; #pragma unroll
;     for (int dd = 0; dd < 2; ++dd) {
;       float x1[8], x2[8], c_[8], s_[8];
;       { const f32x4 ga = *reinterpret_cast<const f32x4*>(gq + 128 + dd * 16), gb = *reinterpret_cast<const f32x4*>(gq + 128 + dd * 16 + 4);
;         const f32x4 gc = *reinterpret_cast<const f32x4*>(gq + 160 + dd * 16), gd = *reinterpret_cast<const f32x4*>(gq + 160 + dd * 16 + 4);
;         const f32x4 ca = *reinterpret_cast<const f32x4*>(tcp + dd * 16), cb = *reinterpret_cast<const f32x4*>(tcp + dd * 16 + 4);
;         const f32x4 sa = *reinterpret_cast<const f32x4*>(tsp + dd * 16), sb = *reinterpret_cast<const f32x4*>(tsp + dd * 16 + 4);
	v_add_f32_e32 v21, v150, v21
	v_mul_f32_e32 v147, v45, v45
	v_fmac_f32_e32 v148, v47, v47
	v_add_f32_e32 v21, v149, v21
	v_fmac_f32_e32 v147, v43, v43
	v_add_f32_e32 v21, v148, v21
	v_add_f32_e32 v21, v147, v21
	v_add_f32_e32 v20, v20, v21
	v_add_f32_e32 v20, v130, v20
	v_add_f32_e32 v20, v129, v20
	v_add_f32_e32 v20, v128, v20
	v_add_f32_e32 v20, v69, v20
	v_add_f32_e32 v20, v68, v20
	v_add_f32_e32 v20, v79, v20
	v_add_f32_e32 v20, v78, v20
	v_mov_b32_e32 v21, v20
	s_nop 1
	v_permlane32_swap_b32_e32 v20, v21
	ds_read_b128 v[16:19], v254 offset:144
	ds_read_b128 v[142:145], v254 offset:128
	v_add_f32_e32 v20, v20, v21
	v_mov_b32_e32 v21, 0x358637bd
	v_fmamk_f32 v20, v20, 0x3baaaaab, v21
	v_mul_f32_e32 v21, 0x4b800000, v20
	v_cmp_gt_f32_e32 vcc, s77, v20
	ds_read_b128 v[146:149], v254 offset:208
	ds_read_b128 v[150:153], v254 offset:192
	v_cndmask_b32_e32 v20, v20, v21, vcc
	v_rsq_f32_e32 v20, v20
	v_mov_b32_e32 v59, v177
	v_lshl_add_u64 v[68:69], v[66:67], 0, v[58:59]
	v_lshl_add_u64 v[78:79], v[68:69], 0, s[10:11]
	global_load_dwordx4 v[212:215], v[78:79], off
	global_load_dwordx4 v[216:219], v[68:69], off offset:16
	global_load_dwordx4 v[220:223], v[68:69], off
	global_load_dwordx4 v[224:227], v[78:79], off offset:16
	global_load_dwordx4 v[228:231], v[78:79], off offset:64
	global_load_dwordx4 v[232:235], v[68:69], off offset:80
	global_load_dwordx4 v[236:239], v[68:69], off offset:64
	global_load_dwordx4 v[240:243], v[78:79], off offset:80
	v_mul_f32_e32 v21, 0x45800000, v20
	v_cndmask_b32_e32 v20, v20, v21, vcc
	v_mul_f32_e32 v20, 0x3dd53b94, v20
	v_mul_f32_e32 v21, v20, v132
	s_waitcnt vmcnt(0) lgkmcnt(0)
	v_mul_f32_e32 v21, v28, v21
	v_mul_f32_e32 v28, v20, v133
	v_mul_f32_e32 v28, v29, v28
	s_nop 0
	v_cvt_pk_bf16_f32 v128, v21, v28
	v_mul_f32_e32 v21, v20, v154
	v_mul_f32_e32 v21, v30, v21
	v_mul_f32_e32 v28, v20, v155
	v_mul_f32_e32 v28, v31, v28
	s_nop 0
	v_cvt_pk_bf16_f32 v129, v21, v28
	v_mul_f32_e32 v21, v20, v162
	ds_read_b128 v[154:157], v254 offset:272
	ds_read_b128 v[158:161], v254 offset:256
	v_mul_f32_e32 v21, v24, v21
	v_mul_f32_e32 v24, v20, v163
	v_mul_f32_e32 v24, v25, v24
	s_nop 0
	v_cvt_pk_bf16_f32 v130, v21, v24
	v_mul_f32_e32 v24, v20, v165
	v_mul_f32_e32 v21, v20, v164
	v_mul_f32_e32 v24, v27, v24
	v_mul_f32_e32 v21, v26, v21
	s_nop 0
	v_cvt_pk_bf16_f32 v131, v21, v24
	v_mul_f32_e32 v24, v20, v167
	v_mul_f32_e32 v21, v20, v166
	v_mul_f32_e32 v24, v139, v24
	v_mul_f32_e32 v21, v138, v21
	s_nop 0
	v_cvt_pk_bf16_f32 v132, v21, v24
	v_mul_f32_e32 v24, v20, v169
	v_mul_f32_e32 v21, v20, v168
	v_mul_f32_e32 v24, v141, v24
	v_mul_f32_e32 v21, v140, v21
	s_nop 0
	v_cvt_pk_bf16_f32 v133, v21, v24
	ds_read_b128 v[24:27], v254 offset:336
	ds_read_b128 v[28:31], v254 offset:320
	v_mul_f32_e32 v21, v20, v126
	v_mul_f32_e32 v21, v134, v21
	v_mul_f32_e32 v59, v20, v125
	v_mul_f32_e32 v59, v135, v59
	s_nop 0
	v_cvt_pk_bf16_f32 v134, v21, v59
	v_mul_f32_e32 v21, v20, v170
	v_mul_f32_e32 v21, v136, v21
	v_mul_f32_e32 v59, v20, v127
	v_mul_f32_e32 v59, v137, v59
	s_nop 0
	v_cvt_pk_bf16_f32 v135, v21, v59
	v_mul_f32_e32 v21, v20, v171
	v_mul_f32_e32 v59, v20, v172
	ds_read_b128 v[162:165], v254 offset:400
	ds_read_b128 v[166:169], v254 offset:384
	v_lshl_add_u64 v[66:67], v[68:69], 0, s[12:13]
	v_and_b32_e32 v209, 63, v96
	v_and_b32_e32 v206, 31, v96
	v_mov_b32_e32 v33, v177
	s_mov_b32 s50, 0
	v_mul_f32_e32 v21, v21, v142
	v_mul_f32_e32 v59, v59, v143
	s_nop 0
	v_cvt_pk_bf16_f32 v136, v21, v59
	v_mul_f32_e32 v21, v20, v173
	v_mul_f32_e32 v21, v21, v144
	v_mul_f32_e32 v59, v20, v174
	v_mul_f32_e32 v59, v59, v145
	s_nop 0
	v_cvt_pk_bf16_f32 v137, v21, v59
	v_mul_f32_e32 v21, v20, v175
	v_mul_f32_e32 v16, v21, v16
	v_mul_f32_e32 v21, v20, v178
	v_mul_f32_e32 v17, v21, v17
	s_nop 0
	v_cvt_pk_bf16_f32 v138, v16, v17
	v_mul_f32_e32 v16, v20, v118
	v_mul_f32_e32 v16, v16, v18
	v_mul_f32_e32 v17, v20, v117
	v_mul_f32_e32 v17, v17, v19
	s_nop 0
	v_cvt_pk_bf16_f32 v139, v16, v17
	v_mul_f32_e32 v16, v20, v120
	v_mul_f32_e32 v16, v16, v150
	v_mul_f32_e32 v17, v20, v119
	v_mul_f32_e32 v17, v17, v151
	s_nop 0
	v_cvt_pk_bf16_f32 v140, v16, v17
	v_mul_f32_e32 v16, v20, v122
	v_mul_f32_e32 v16, v16, v152
	v_mul_f32_e32 v17, v20, v121
	v_mul_f32_e32 v17, v17, v153
	s_nop 0
	v_cvt_pk_bf16_f32 v141, v16, v17
	v_mul_f32_e32 v16, v20, v124
	v_mul_f32_e32 v16, v16, v146
	v_mul_f32_e32 v17, v20, v123
	v_mul_f32_e32 v17, v17, v147
	s_nop 0
	v_cvt_pk_bf16_f32 v142, v16, v17
	v_mul_f32_e32 v16, v20, v111
	v_mul_f32_e32 v16, v16, v148
	v_mul_f32_e32 v17, v20, v110
	v_mul_f32_e32 v17, v17, v149
	s_nop 0
	v_cvt_pk_bf16_f32 v143, v16, v17
	v_mul_f32_e32 v16, v20, v113
	s_waitcnt vmcnt(0) lgkmcnt(0)
; __device__ __forceinline__ void attn_body(const u16* __restrict__ Qb, const u16* __restrict__ Kn, const u16* __restrict__ Kr,
;                                           u16* __restrict__ Ob, char* lds, int tid, const float* __restrict__ gq_, const float* __restrict__ tab_, int qpos0, float negM) {
;     ...
;       const f32x4 g0 = *reinterpret_cast<const f32x4*>(gq + d0 * 16), g1 = *reinterpret_cast<const f32x4*>(gq + d0 * 16 + 4);
;       const u32x4 w = qw[d0];
;       const u32x4 o = {cvtpk(bflo(w[0]) * rq * g0[0], bfhi(w[0]) * rq * g0[1]), cvtpk(bflo(w[1]) * rq * g0[2], bfhi(w[1]) * rq * g0[3]),
;                        cvtpk(bflo(w[2]) * rq * g1[0], bfhi(w[2]) * rq * g1[1]), cvtpk(bflo(w[3]) * rq * g1[2], bfhi(w[3]) * rq * g1[3])};
;       qr[d0] = *reinterpret_cast<const bf16x8*>(&o); }
;     const float* tcp = tab_ + (size_t)(qpos0 + wid * 32 + r32) * 32 + hi * 8; const float* tsp = tcp + SEQ * 32;
; #pragma unroll
;     for (int dd = 0; dd < 2; ++dd) {
;       float x1[8], x2[8], c_[8], s_[8];
;       { const f32x4 ga = *reinterpret_cast<const f32x4*>(gq + 128 + dd * 16), gb = *reinterpret_cast<const f32x4*>(gq + 128 + dd * 16 + 4);
;         const f32x4 gc = *reinterpret_cast<const f32x4*>(gq + 160 + dd * 16), gd = *reinterpret_cast<const f32x4*>(gq + 160 + dd * 16 + 4);
;         const f32x4 ca = *reinterpret_cast<const f32x4*>(tcp + dd * 16), cb = *reinterpret_cast<const f32x4*>(tcp + dd * 16 + 4);
;         const f32x4 sa = *reinterpret_cast<const f32x4*>(tsp + dd * 16), sb = *reinterpret_cast<const f32x4*>(tsp + dd * 16 + 4);
;         const u32x4 w1 = qw[8 + dd], w2 = qw[10 + dd];
; #pragma unroll
;         for (int e = 0; e < 4; ++e) {
;           const float g1lo = e < 2 ? ga[2 * e] : gb[2 * e - 4], g1hi = e < 2 ? ga[2 * e + 1] : gb[2 * e - 3];
;           const float g2lo = e < 2 ? gc[2 * e] : gd[2 * e - 4], g2hi = e < 2 ? gc[2 * e + 1] : gd[2 * e - 3];
;           x1[2 * e] = bflo(w1[e]) * rq * g1lo; x1[2 * e + 1] = bfhi(w1[e]) * rq * g1hi;
;           x2[2 * e] = bflo(w2[e]) * rq * g2lo; x2[2 * e + 1] = bfhi(w2[e]) * rq * g2hi;
;           c_[2 * e] = e < 2 ? ca[2 * e] : cb[2 * e - 4]; c_[2 * e + 1] = e < 2 ? ca[2 * e + 1] : cb[2 * e - 3];
;           s_[2 * e] = e < 2 ? sa[2 * e] : sb[2 * e - 4]; s_[2 * e + 1] = e < 2 ? sa[2 * e + 1] : sb[2 * e - 3]; } }
;       float y1[8], y2[8];
; #pragma unroll
	v_mul_f32_e32 v16, v16, v158
	v_mul_f32_e32 v17, v20, v112
	v_mul_f32_e32 v17, v17, v159
	s_nop 0
	v_cvt_pk_bf16_f32 v144, v16, v17
	v_mul_f32_e32 v16, v20, v115
	v_mul_f32_e32 v16, v16, v160
	v_mul_f32_e32 v17, v20, v114
	ds_read_b128 v[118:121], v254 offset:464
	ds_read_b128 v[122:125], v254 offset:448
	v_mul_f32_e32 v17, v17, v161
	s_nop 0
	v_cvt_pk_bf16_f32 v145, v16, v17
	v_mul_f32_e32 v16, v20, v116
	v_mul_f32_e32 v16, v16, v154
	v_mul_f32_e32 v17, v20, v90
	v_mul_f32_e32 v17, v17, v155
	s_nop 0
	v_cvt_pk_bf16_f32 v146, v16, v17
	v_mul_f32_e32 v16, v20, v98
	v_mul_f32_e32 v16, v16, v156
	v_mul_f32_e32 v17, v20, v94
	v_mul_f32_e32 v17, v17, v157
	s_nop 0
	v_cvt_pk_bf16_f32 v147, v16, v17
	v_mul_f32_e32 v16, v20, v103
	v_mul_f32_e32 v16, v16, v28
	v_mul_f32_e32 v17, v20, v99
	v_mul_f32_e32 v17, v17, v29
	s_nop 0
	v_cvt_pk_bf16_f32 v148, v16, v17
	v_mul_f32_e32 v16, v20, v106
	ds_read_b128 v[110:113], v254 offset:656
	ds_read_b128 v[114:117], v254 offset:640
	ds_read_b128 v[170:173], v254 offset:528
	ds_read_b128 v[178:181], v254 offset:512
	v_mul_f32_e32 v16, v16, v30
	v_mul_f32_e32 v17, v20, v104
	v_mul_f32_e32 v17, v17, v31
	s_nop 0
	v_cvt_pk_bf16_f32 v149, v16, v17
	v_mul_f32_e32 v16, v20, v108
	v_mul_f32_e32 v16, v16, v24
	v_mul_f32_e32 v17, v20, v107
	v_add_co_u32_e32 v98, vcc, s78, v68
	v_mul_f32_e32 v17, v17, v25
	s_nop 0
	v_cvt_pk_bf16_f32 v150, v16, v17
	v_mul_f32_e32 v16, v20, v109
	v_addc_co_u32_e32 v99, vcc, 0, v69, vcc
	v_mul_f32_e32 v21, v16, v26
	v_mov_b32_e32 v28, v212
	v_mov_b32_e32 v29, v213
	v_mov_b32_e32 v30, v214
	v_mov_b32_e32 v31, v215
	v_mov_b32_e32 v16, v216
	v_mov_b32_e32 v17, v217
	v_mov_b32_e32 v18, v218
	v_mov_b32_e32 v19, v219
	v_mov_b32_e32 v106, v220
	v_mov_b32_e32 v107, v221
	v_mov_b32_e32 v108, v222
	v_mov_b32_e32 v109, v223
	v_mul_f32_e32 v24, v20, v82
	v_mul_f32_e32 v24, v24, v27
	s_nop 0
	v_cvt_pk_bf16_f32 v151, v21, v24
	v_mul_f32_e32 v21, v20, v84
	v_mul_f32_e32 v21, v21, v166
	v_mul_f32_e32 v24, v20, v83
	v_mul_f32_e32 v24, v24, v167
	s_nop 0
	v_cvt_pk_bf16_f32 v152, v21, v24
	v_mul_f32_e32 v21, v20, v86
	v_mul_f32_e32 v21, v21, v168
	v_mul_f32_e32 v24, v20, v85
	v_mul_f32_e32 v24, v24, v169
	s_nop 0
	v_cvt_pk_bf16_f32 v153, v21, v24
	v_mul_f32_e32 v21, v20, v88
	v_mul_f32_e32 v21, v21, v162
	v_mul_f32_e32 v24, v20, v87
	v_mul_f32_e32 v24, v24, v163
	s_nop 0
	v_cvt_pk_bf16_f32 v154, v21, v24
	v_mul_f32_e32 v21, v20, v91
	v_mul_f32_e32 v21, v21, v164
	v_mul_f32_e32 v24, v20, v89
	v_mul_f32_e32 v24, v24, v165
	s_nop 0
	v_cvt_pk_bf16_f32 v155, v21, v24
	v_mul_f32_e32 v21, v20, v95
	v_mul_f32_e32 v24, v20, v92
	v_mul_f32_e32 v59, v20, v93
	s_waitcnt vmcnt(0) lgkmcnt(0)
	v_mul_f32_e32 v21, v21, v122
	v_mul_f32_e32 v24, v24, v123
	s_nop 0
	v_cvt_pk_bf16_f32 v156, v21, v24
	v_mul_f32_e32 v21, v20, v100
	v_mul_f32_e32 v21, v21, v124
	v_mov_b32_e32 v24, v224
	v_mov_b32_e32 v25, v225
	v_mov_b32_e32 v26, v226
	v_mov_b32_e32 v27, v227
	v_mul_f32_e32 v59, v59, v125
	s_nop 0
	v_cvt_pk_bf16_f32 v157, v21, v59
	v_mul_f32_e32 v21, v20, v101
	v_mul_f32_e32 v21, v21, v118
	v_mul_f32_e32 v59, v20, v97
	v_mul_f32_e32 v59, v59, v119
	s_nop 0
	v_cvt_pk_bf16_f32 v158, v21, v59
	v_mul_f32_e32 v21, v20, v105
	v_mul_f32_e32 v21, v21, v120
	v_pk_mul_f32 v[74:75], v[20:21], v[74:75] op_sel_hi:[0,1]
	v_mul_f32_e32 v59, v20, v102
	v_pk_mul_f32 v[70:71], v[20:21], v[70:71] op_sel_hi:[0,1]
	v_mul_f32_e32 v59, v59, v121
	v_mov_b32_e32 v79, v178
	v_mov_b32_e32 v178, v115
	v_pk_mul_f32 v[90:91], v[74:75], v[178:179]
	v_mov_b32_e32 v75, v180
	v_mov_b32_e32 v180, v117
	v_pk_mul_f32 v[76:77], v[20:21], v[76:77] op_sel_hi:[0,1]
	v_mov_b32_e32 v78, v114
	v_pk_mul_f32 v[72:73], v[20:21], v[72:73] op_sel_hi:[0,1]
	v_mov_b32_e32 v74, v116
	v_pk_mul_f32 v[100:101], v[70:71], v[180:181]
	v_pk_mul_f32 v[64:65], v[20:21], v[64:65] op_sel_hi:[0,1]
	v_mov_b32_e32 v70, v110
	v_mov_b32_e32 v71, v170
	s_nop 0
	v_cvt_pk_bf16_f32 v159, v21, v59
	v_pk_mul_f32 v[78:79], v[76:77], v[78:79]
	v_pk_mul_f32 v[94:95], v[72:73], v[74:75]
	v_pk_mul_f32 v[102:103], v[64:65], v[70:71]
	ds_read_b128 v[70:73], v254 offset:720
	ds_read_b128 v[74:77], v254 offset:704
	ds_read_b128 v[82:85], v254 offset:592
	ds_read_b128 v[86:89], v254 offset:576
	v_pk_mul_f32 v[58:59], v[20:21], v[62:63] op_sel_hi:[0,1]
	v_mov_b32_e32 v62, v112
	v_mov_b32_e32 v63, v172
	v_pk_mul_f32 v[104:105], v[58:59], v[62:63]
	v_mov_b32_e32 v62, v28
	v_mov_b32_e32 v63, v106
	v_pk_mul_f32 v[62:63], v[78:79], v[62:63]
	v_pk_mul_f32 v[22:23], v[20:21], v[22:23] op_sel_hi:[0,1]
	v_pk_mul_f32 v[58:59], v[20:21], v[60:61] op_sel_hi:[0,1]
	v_sub_f32_e32 v21, v63, v62
	v_mov_b32_e32 v62, v106
	v_mov_b32_e32 v63, v28
	v_pk_mul_f32 v[62:63], v[78:79], v[62:63]
	v_mov_b32_e32 v106, v29
	v_mov_b32_e32 v172, v113
	v_add_f32_e32 v78, v62, v63
	v_pk_mul_f32 v[62:63], v[90:91], v[106:107]
	v_mov_b32_e32 v28, v107
	v_mov_b32_e32 v170, v111
	v_pk_mul_f32 v[110:111], v[58:59], v[172:173]
	v_mov_b32_e32 v58, v228
	v_mov_b32_e32 v59, v229
	v_mov_b32_e32 v60, v230
	v_mov_b32_e32 v61, v231
	v_sub_f32_e32 v79, v63, v62
	v_pk_mul_f32 v[28:29], v[90:91], v[28:29]
	v_mov_b32_e32 v62, v232
	v_mov_b32_e32 v63, v233
	v_mov_b32_e32 v64, v234
	v_mov_b32_e32 v65, v235
	v_mov_b32_e32 v90, v236
	v_mov_b32_e32 v91, v237
	v_mov_b32_e32 v92, v238
	v_mov_b32_e32 v93, v239
	v_add_f32_e32 v97, v28, v29
	v_mov_b32_e32 v28, v30
	v_mov_b32_e32 v29, v108
	v_pk_mul_f32 v[28:29], v[94:95], v[28:29]
	v_pk_mul_f32 v[22:23], v[22:23], v[170:171]
	v_sub_f32_e32 v68, v29, v28
	v_mov_b32_e32 v28, v108
	v_mov_b32_e32 v29, v30
	v_pk_mul_f32 v[28:29], v[94:95], v[28:29]
	v_mov_b32_e32 v108, v31
	v_add_f32_e32 v69, v28, v29
	v_pk_mul_f32 v[28:29], v[100:101], v[108:109]
	v_mov_b32_e32 v30, v109
	v_sub_f32_e32 v94, v29, v28
	v_pk_mul_f32 v[28:29], v[100:101], v[30:31]
	s_nop 0
	v_cvt_pk_bf16_f32 v164, v21, v79
	v_pk_mul_f32 v[46:47], v[20:21], v[46:47] op_sel_hi:[0,1]
	v_add_f32_e32 v95, v28, v29
	v_mov_b32_e32 v28, v240
	v_mov_b32_e32 v29, v241
	v_mov_b32_e32 v30, v242
	v_mov_b32_e32 v31, v243
	v_mov_b32_e32 v67, v16
	v_pk_mul_f32 v[44:45], v[20:21], v[44:45] op_sel_hi:[0,1]
	s_waitcnt vmcnt(0) lgkmcnt(0)
	s_nop 0
	v_cvt_pk_bf16_f32 v165, v68, v94
	s_nop 0
	v_cvt_pk_bf16_f32 v160, v78, v97
	s_waitcnt vmcnt(0) lgkmcnt(0)
	v_mov_b32_e32 v66, v24
	v_pk_mul_f32 v[66:67], v[102:103], v[66:67]
	s_nop 0
	v_cvt_pk_bf16_f32 v161, v69, v95
	s_barrier
; __device__ __forceinline__ int v_rd_base(int lane) { return ((lane & 3) << 3) | (((lane >> 2) & 3) << 6) | (((lane >> 4) & 1) << 5) | (((lane >> 5) & 1) << 8); }
; #define AISSUE(k0, soff) do { const char* kb_ = (const char*)Kn + (size_t)(k0) * 4096; const char* rb_ = (const char*)Kr + (size_t)(k0) * 1024; \
;     char* st_ = lds + (soff) + tid * 16; \
;     GLDS(kb_ + vkn0, st_ + KOFF); GLDS(kb_ + vkn1, st_ + KOFF + 8192); GLDS(rb_ + vkr, st_ + KOFF + KROPE_OFF); \
;     GLDS(kb_ + vv0, st_); GLDS(kb_ + vv1, st_ + 8192); } while (0)
; #define WAITV(n) asm volatile("s_waitcnt vmcnt(" #n ")" ::: "memory")
; #define TBAR() do { __builtin_amdgcn_s_barrier(); SBAR(); } while (0)
; __device__ __forceinline__ void qkt(f32x16& p0, f32x16& p1, const char* Ks, const bf16x8* qr, int r32, int hi, float negM) {
;     ...
;   const char* kn = Ks + r32 * 256; const int xn = r32 & 15;
; #pragma unroll
;   for (int d0 = 0; d0 < 8; ++d0) { const int off = ((d0 * 2 + hi) ^ xn) << 4;
;     bf16x8 b0 = *reinterpret_cast<const bf16x8*>(kn + off);
;     bf16x8 b1 = *reinterpret_cast<const bf16x8*>(kn + 32 * 256 + off);
;     p0 = __builtin_amdgcn_mfma_f32_32x32x16_bf16(b0, qr[d0], p0, 0, 0, 0);
;     p1 = __builtin_amdgcn_mfma_f32_32x32x16_bf16(b1, qr[d0], p1, 0, 0, 0); }
; __device__ __forceinline__ void attn_body(const u16* __restrict__ Qb, const u16* __restrict__ Kn, const u16* __restrict__ Kr,
;                                           u16* __restrict__ Ob, char* lds, int tid, const float* __restrict__ gq_, const float* __restrict__ tab_, int qpos0, float negM) {
;     ...
;       float y1[8], y2[8];
; #pragma unroll
;       for (int e = 0; e < 8; ++e) { y1[e] = x1[e] * c_[e] - x2[e] * s_[e]; y2[e] = x2[e] * c_[e] + x1[e] * s_[e]; }
;       const u32x4 o1 = {cvtpk(y1[0], y1[1]), cvtpk(y1[2], y1[3]), cvtpk(y1[4], y1[5]), cvtpk(y1[6], y1[7])};
;       const u32x4 o2 = {cvtpk(y2[0], y2[1]), cvtpk(y2[2], y2[3]), cvtpk(y2[4], y2[5]), cvtpk(y2[6], y2[7])};
;       qr[8 + dd] = *reinterpret_cast<const bf16x8*>(&o1); qr[10 + dd] = *reinterpret_cast<const bf16x8*>(&o2); }
;   }
;   const int vrb = (int)(uintptr_t)lds + v_rd_base(lane);
;   f32x16 pA0, pA1, pB0, pB1; bf16x8 pa0, pa1, pa2, pa3; constexpr int NT = SEQ / KVBLK;
;   WAITV(0); TBAR();
;   AISSUE(KVBLK, STG);
;   qkt(pA0, pA1, lds + KOFF, qr, r32, hi, negM); partialSM(pA0);
	v_sub_f32_e32 v98, v67, v66
	v_mov_b32_e32 v66, v16
	v_mov_b32_e32 v67, v24
	v_pk_mul_f32 v[66:67], v[102:103], v[66:67]
	v_mov_b32_e32 v16, v25
	v_mov_b32_e32 v24, v17
	v_add_f32_e32 v99, v66, v67
	v_pk_mul_f32 v[66:67], v[22:23], v[16:17]
	v_pk_mul_f32 v[16:17], v[22:23], v[24:25]
	v_sub_f32_e32 v66, v67, v66
	v_add_f32_e32 v22, v16, v17
	v_mov_b32_e32 v16, v26
	v_mov_b32_e32 v17, v18
	v_pk_mul_f32 v[16:17], v[104:105], v[16:17]
	s_nop 0
	v_cvt_pk_bf16_f32 v162, v99, v22
	s_nop 0
	v_cvt_pk_bf16_f32 v166, v98, v66
	v_mov_b32_e32 v25, v88
	v_sub_f32_e32 v23, v17, v16
	v_mov_b32_e32 v16, v18
	v_mov_b32_e32 v17, v26
	v_pk_mul_f32 v[16:17], v[104:105], v[16:17]
	v_mov_b32_e32 v18, v27
	v_add_f32_e32 v24, v16, v17
	v_pk_mul_f32 v[16:17], v[110:111], v[18:19]
	v_mov_b32_e32 v26, v19
	v_sub_f32_e32 v18, v17, v16
	v_pk_mul_f32 v[16:17], v[110:111], v[26:27]
	s_nop 0
	v_cvt_pk_bf16_f32 v167, v23, v18
	v_mov_b32_e32 v18, v74
	v_add_f32_e32 v16, v16, v17
	s_nop 0
	v_cvt_pk_bf16_f32 v163, v24, v16
	v_pk_mul_f32 v[16:17], v[20:21], v[56:57] op_sel_hi:[0,1]
	v_mov_b32_e32 v19, v86
	v_pk_mul_f32 v[22:23], v[20:21], v[52:53] op_sel_hi:[0,1]
	v_mov_b32_e32 v24, v76
	v_pk_mul_f32 v[16:17], v[16:17], v[18:19]
	v_pk_mul_f32 v[18:19], v[20:21], v[54:55] op_sel_hi:[0,1]
	v_pk_mul_f32 v[22:23], v[22:23], v[24:25]
	v_pk_mul_f32 v[24:25], v[20:21], v[50:51] op_sel_hi:[0,1]
	v_pk_mul_f32 v[26:27], v[20:21], v[48:49] op_sel_hi:[0,1]
	v_mov_b32_e32 v48, v70
	v_mov_b32_e32 v49, v82
	v_pk_mul_f32 v[20:21], v[20:21], v[42:43] op_sel_hi:[0,1]
	v_mov_b32_e32 v42, v58
	v_mov_b32_e32 v43, v90
	v_pk_mul_f32 v[26:27], v[26:27], v[48:49]
	v_mov_b32_e32 v48, v72
	v_mov_b32_e32 v49, v84
	v_pk_mul_f32 v[42:43], v[16:17], v[42:43]
	v_mov_b32_e32 v86, v75
	v_pk_mul_f32 v[44:45], v[44:45], v[48:49]
	v_sub_f32_e32 v48, v43, v42
	v_mov_b32_e32 v42, v90
	v_mov_b32_e32 v43, v58
	v_pk_mul_f32 v[18:19], v[18:19], v[86:87]
	v_pk_mul_f32 v[16:17], v[16:17], v[42:43]
	v_mov_b32_e32 v90, v59
	v_add_f32_e32 v42, v16, v17
	v_pk_mul_f32 v[16:17], v[18:19], v[90:91]
	v_mov_b32_e32 v58, v91
	v_sub_f32_e32 v43, v17, v16
	v_pk_mul_f32 v[16:17], v[18:19], v[58:59]
	v_mov_b32_e32 v88, v77
	v_add_f32_e32 v18, v16, v17
	v_mov_b32_e32 v16, v60
	v_mov_b32_e32 v17, v92
	v_pk_mul_f32 v[16:17], v[22:23], v[16:17]
	v_pk_mul_f32 v[24:25], v[24:25], v[88:89]
	v_sub_f32_e32 v19, v17, v16
	v_mov_b32_e32 v16, v92
	v_mov_b32_e32 v17, v60
	v_pk_mul_f32 v[16:17], v[22:23], v[16:17]
	v_mov_b32_e32 v92, v61
	v_add_f32_e32 v22, v16, v17
	v_pk_mul_f32 v[16:17], v[24:25], v[92:93]
	v_mov_b32_e32 v60, v93
	v_sub_f32_e32 v23, v17, v16
	v_pk_mul_f32 v[16:17], v[24:25], v[60:61]
	v_mov_b32_e32 v82, v71
	v_add_f32_e32 v24, v16, v17
	v_mov_b32_e32 v16, v28
	v_mov_b32_e32 v17, v62
	v_pk_mul_f32 v[16:17], v[26:27], v[16:17]
	v_pk_mul_f32 v[46:47], v[46:47], v[82:83]
	v_sub_f32_e32 v25, v17, v16
	v_mov_b32_e32 v16, v62
	v_mov_b32_e32 v17, v28
	v_pk_mul_f32 v[16:17], v[26:27], v[16:17]
	v_mov_b32_e32 v62, v29
	v_add_f32_e32 v26, v16, v17
	v_pk_mul_f32 v[16:17], v[46:47], v[62:63]
	v_mov_b32_e32 v28, v63
	v_sub_f32_e32 v27, v17, v16
	v_pk_mul_f32 v[16:17], v[46:47], v[28:29]
	v_mov_b32_e32 v84, v73
	v_add_f32_e32 v28, v16, v17
	v_mov_b32_e32 v16, v30
	v_mov_b32_e32 v17, v64
	v_pk_mul_f32 v[16:17], v[44:45], v[16:17]
	v_pk_mul_f32 v[20:21], v[20:21], v[84:85]
	v_sub_f32_e32 v29, v17, v16
	v_mov_b32_e32 v16, v64
	v_mov_b32_e32 v17, v30
	v_pk_mul_f32 v[16:17], v[44:45], v[16:17]
	v_mov_b32_e32 v64, v31
	v_add_f32_e32 v44, v16, v17
	v_pk_mul_f32 v[16:17], v[20:21], v[64:65]
	v_mov_b32_e32 v30, v65
	v_sub_f32_e32 v45, v17, v16
	v_pk_mul_f32 v[16:17], v[20:21], v[30:31]
	s_nop 0
	v_cvt_pk_bf16_f32 v168, v42, v18
	v_lshlrev_b32_e32 v18, 1, v96
	v_add_f32_e32 v16, v16, v17
	v_lshlrev_b32_e32 v17, 4, v96
	s_nop 0
	v_cvt_pk_bf16_f32 v171, v44, v16
	v_lshlrev_b32_e32 v16, 3, v209
	v_and_b32_e32 v17, 0xc0, v17
	v_and_or_b32 v17, v16, 24, v17
	v_and_b32_e32 v18, 32, v18
	v_and_b32_e32 v16, 0x100, v16
	v_or3_b32 v212, v17, v18, v16
	s_nop 0
	v_cvt_pk_bf16_f32 v172, v48, v43
	s_nop 0
	v_cvt_pk_bf16_f32 v173, v19, v23
	s_nop 0
	v_cvt_pk_bf16_f32 v174, v25, v27
	s_nop 0
	v_cvt_pk_bf16_f32 v175, v29, v45
	s_nop 0
	v_cvt_pk_bf16_f32 v169, v22, v24
	s_nop 0
	v_cvt_pk_bf16_f32 v170, v26, v28
	v_add_u32_e32 v16, 0xe000, v211
	s_add_u32 s48, s48, 0x40000
	v_readfirstlane_b32 s51, v16
	v_add_u32_e32 v16, 0x10000, v211
	s_addc_u32 s49, s49, 0
	s_mov_b32 m0, s51
	v_readfirstlane_b32 s51, v16
	v_add_u32_e32 v19, 0x12000, v211
	global_load_lds_dwordx4 v176, s[48:49]
	s_mov_b32 m0, s51
	v_readfirstlane_b32 s51, v19
	v_add_u32_e32 v18, 0xa000, v211
	global_load_lds_dwordx4 v32, s[48:49]
	v_lshl_add_u64 v[16:17], v[40:41], 0, s[14:15]
	s_mov_b32 m0, s51
	v_readfirstlane_b32 s51, v18
	global_load_lds_dwordx4 v[16:17], off
	v_add_u32_e32 v16, 0xc000, v211
	s_mov_b32 m0, s51
	v_readfirstlane_b32 s51, v16
	global_load_lds_dwordx4 v80, s[48:49]
	s_mov_b32 m0, s51
	s_nop 0
	global_load_lds_dwordx4 v81, s[48:49]
	s_setprio 1
	v_bitop3_b32 v16, v207, v96, 15 bitop3:0x78
	v_lshlrev_b32_e32 v213, 8, v206
	v_lshlrev_b32_e32 v214, 4, v16
	v_or_b32_e32 v16, v213, v214
	ds_read_b128 v[40:43], v16 offset:16384
	ds_read_b128 v[44:47], v16 offset:24576
	v_and_b32_e32 v48, 15, v96
	v_lshlrev_b32_e32 v222, 7, v206
	s_waitcnt lgkmcnt(0)
	v_mfma_f32_32x32x16_bf16 v[16:31], v[40:43], v[128:131], v[0:15]
	v_bitop3_b32 v40, v207, v48, 2 bitop3:0x36
	v_lshlrev_b32_e32 v215, 4, v40
	v_mfma_f32_32x32x16_bf16 v[80:95], v[44:47], v[128:131], v[0:15]
	v_or_b32_e32 v44, v213, v215
	ds_read_b128 v[40:43], v44 offset:16384
	ds_read_b128 v[44:47], v44 offset:24576
	s_waitcnt lgkmcnt(0)
; #define AISSUE(k0, soff) do { const char* kb_ = (const char*)Kn + (size_t)(k0) * 4096; const char* rb_ = (const char*)Kr + (size_t)(k0) * 1024; \
;     char* st_ = lds + (soff) + tid * 16; \
;     GLDS(kb_ + vkn0, st_ + KOFF); GLDS(kb_ + vkn1, st_ + KOFF + 8192); GLDS(rb_ + vkr, st_ + KOFF + KROPE_OFF); \
;     GLDS(kb_ + vv0, st_); GLDS(kb_ + vv1, st_ + 8192); } while (0)
; #define WAITV(n) asm volatile("s_waitcnt vmcnt(" #n ")" ::: "memory")
; #define TBAR() do { __builtin_amdgcn_s_barrier(); SBAR(); } while (0)
; __device__ __forceinline__ void qkt(f32x16& p0, f32x16& p1, const char* Ks, const bf16x8* qr, int r32, int hi, float negM) {
; #pragma unroll
;   for (int r = 0; r < 16; ++r) { p0[r] = negM; p1[r] = negM; }
;   __builtin_amdgcn_s_setprio(1);
;   const char* kn = Ks + r32 * 256; const int xn = r32 & 15;
; #pragma unroll
;   for (int d0 = 0; d0 < 8; ++d0) { const int off = ((d0 * 2 + hi) ^ xn) << 4;
;     bf16x8 b0 = *reinterpret_cast<const bf16x8*>(kn + off);
;     bf16x8 b1 = *reinterpret_cast<const bf16x8*>(kn + 32 * 256 + off);
;     p0 = __builtin_amdgcn_mfma_f32_32x32x16_bf16(b0, qr[d0], p0, 0, 0, 0);
;     p1 = __builtin_amdgcn_mfma_f32_32x32x16_bf16(b1, qr[d0], p1, 0, 0, 0); }
;   const char* kr = Ks + KROPE_OFF + r32 * 128; const int xr = (r32 >> 1) & 7;
; #pragma unroll
;   for (int d0 = 8; d0 < 12; ++d0) { const int off = (((d0 - 8) * 2 + hi) ^ xr) << 4;
;     bf16x8 b0 = *reinterpret_cast<const bf16x8*>(kr + off);
;     bf16x8 b1 = *reinterpret_cast<const bf16x8*>(kr + 32 * 128 + off);
;     p0 = __builtin_amdgcn_mfma_f32_32x32x16_bf16(b0, qr[d0], p0, 0, 0, 0);
;     p1 = __builtin_amdgcn_mfma_f32_32x32x16_bf16(b1, qr[d0], p1, 0, 0, 0); }
;   __builtin_amdgcn_s_setprio(0);
; }
; __device__ __forceinline__ void attn_body(const u16* __restrict__ Qb, const u16* __restrict__ Kn, const u16* __restrict__ Kr,
;                                           u16* __restrict__ Ob, char* lds, int tid, const float* __restrict__ gq_, const float* __restrict__ tab_, int qpos0, float negM) {
;     ...
;   f32x16 pA0, pA1, pB0, pB1; bf16x8 pa0, pa1, pa2, pa3; constexpr int NT = SEQ / KVBLK;
;   WAITV(0); TBAR();
;   AISSUE(KVBLK, STG);
;   qkt(pA0, pA1, lds + KOFF, qr, r32, hi, negM); partialSM(pA0);
;   int prv = 0, cur = STG, nxt = 2 * STG;
	v_mfma_f32_32x32x16_bf16 v[16:31], v[40:43], v[132:135], v[16:31]
	v_bitop3_b32 v40, v207, v48, 4 bitop3:0x36
	v_lshlrev_b32_e32 v216, 4, v40
	v_mfma_f32_32x32x16_bf16 v[80:95], v[44:47], v[132:135], v[80:95]
	v_or_b32_e32 v44, v213, v216
	ds_read_b128 v[40:43], v44 offset:16384
	ds_read_b128 v[44:47], v44 offset:24576
	s_waitcnt lgkmcnt(0)
	v_mfma_f32_32x32x16_bf16 v[16:31], v[40:43], v[136:139], v[16:31]
	v_bitop3_b32 v40, v207, v48, 6 bitop3:0x36
	v_lshlrev_b32_e32 v217, 4, v40
	v_mfma_f32_32x32x16_bf16 v[80:95], v[44:47], v[136:139], v[80:95]
	v_or_b32_e32 v44, v213, v217
	ds_read_b128 v[40:43], v44 offset:16384
	ds_read_b128 v[44:47], v44 offset:24576
	s_waitcnt lgkmcnt(0)
	v_mfma_f32_32x32x16_bf16 v[16:31], v[40:43], v[140:143], v[16:31]
	v_bitop3_b32 v40, v207, v48, 8 bitop3:0x36
	v_lshlrev_b32_e32 v218, 4, v40
	v_mfma_f32_32x32x16_bf16 v[80:95], v[44:47], v[140:143], v[80:95]
	v_or_b32_e32 v44, v213, v218
	ds_read_b128 v[40:43], v44 offset:16384
	ds_read_b128 v[44:47], v44 offset:24576
	s_waitcnt lgkmcnt(0)
	v_mfma_f32_32x32x16_bf16 v[16:31], v[40:43], v[144:147], v[16:31]
	v_bitop3_b32 v40, v207, v48, 10 bitop3:0x36
	v_lshlrev_b32_e32 v219, 4, v40
	v_mfma_f32_32x32x16_bf16 v[80:95], v[44:47], v[144:147], v[80:95]
	v_or_b32_e32 v44, v213, v219
	ds_read_b128 v[40:43], v44 offset:16384
	ds_read_b128 v[44:47], v44 offset:24576
	s_waitcnt lgkmcnt(0)
	v_mfma_f32_32x32x16_bf16 v[16:31], v[40:43], v[148:151], v[16:31]
	v_bitop3_b32 v40, v207, v48, 12 bitop3:0x36
	v_lshlrev_b32_e32 v220, 4, v40
	v_mfma_f32_32x32x16_bf16 v[80:95], v[44:47], v[148:151], v[80:95]
	v_or_b32_e32 v44, v213, v220
	ds_read_b128 v[40:43], v44 offset:16384
	ds_read_b128 v[44:47], v44 offset:24576
	s_waitcnt lgkmcnt(0)
	v_mfma_f32_32x32x16_bf16 v[16:31], v[40:43], v[152:155], v[16:31]
	v_bitop3_b32 v40, v207, v48, 14 bitop3:0x36
	v_lshlrev_b32_e32 v221, 4, v40
	v_bfe_u32 v48, v96, 1, 3
	v_mfma_f32_32x32x16_bf16 v[80:95], v[44:47], v[152:155], v[80:95]
	v_or_b32_e32 v44, v213, v221
	ds_read_b128 v[40:43], v44 offset:16384
	ds_read_b128 v[44:47], v44 offset:24576
	s_waitcnt lgkmcnt(0)
	v_mfma_f32_32x32x16_bf16 v[16:31], v[40:43], v[156:159], v[16:31]
	v_lshrrev_b32_e32 v40, 1, v96
	v_bitop3_b32 v40, v207, v40, 7 bitop3:0x78
	v_lshlrev_b32_e32 v223, 4, v40
	v_mfma_f32_32x32x16_bf16 v[80:95], v[44:47], v[156:159], v[80:95]
	v_or_b32_e32 v44, v222, v223
	ds_read_b128 v[40:43], v44 offset:32768
	ds_read_b128 v[44:47], v44 offset:36864
	s_waitcnt lgkmcnt(0)
	v_mfma_f32_32x32x16_bf16 v[16:31], v[40:43], v[164:167], v[16:31]
	v_bitop3_b32 v40, v207, v48, 2 bitop3:0x36
	v_lshlrev_b32_e32 v224, 4, v40
	v_mfma_f32_32x32x16_bf16 v[80:95], v[44:47], v[164:167], v[80:95]
	v_or_b32_e32 v44, v222, v224
	ds_read_b128 v[40:43], v44 offset:32768
	ds_read_b128 v[44:47], v44 offset:36864
	s_waitcnt lgkmcnt(0)
	v_mfma_f32_32x32x16_bf16 v[16:31], v[40:43], v[172:175], v[16:31]
	v_bitop3_b32 v40, v207, v48, 4 bitop3:0x36
	v_lshlrev_b32_e32 v225, 4, v40
	v_mfma_f32_32x32x16_bf16 v[80:95], v[44:47], v[172:175], v[80:95]
	v_or_b32_e32 v44, v222, v225
	ds_read_b128 v[40:43], v44 offset:32768
	ds_read_b128 v[44:47], v44 offset:36864
	s_waitcnt lgkmcnt(0)
	v_mfma_f32_32x32x16_bf16 v[16:31], v[40:43], v[160:163], v[16:31]
	v_bitop3_b32 v40, v207, v48, 6 bitop3:0x36
	v_lshlrev_b32_e32 v226, 4, v40
	v_mfma_f32_32x32x16_bf16 v[80:95], v[44:47], v[160:163], v[80:95]
	v_or_b32_e32 v44, v222, v226
	ds_read_b128 v[40:43], v44 offset:32768
	ds_read_b128 v[44:47], v44 offset:36864
	s_waitcnt lgkmcnt(0)
	v_mfma_f32_32x32x16_bf16 v[16:31], v[40:43], v[168:171], v[16:31]
	v_mfma_f32_32x32x16_bf16 v[80:95], v[44:47], v[168:171], v[80:95]
	s_setprio 0
	s_nop 9
	v_exp_f32_e32 v240, v16
	v_exp_f32_e32 v242, v17
	v_exp_f32_e32 v238, v18
	v_exp_f32_e32 v241, v19
	v_exp_f32_e32 v236, v20
	v_exp_f32_e32 v239, v21
	v_exp_f32_e32 v235, v22
	v_exp_f32_e32 v237, v23
	v_exp_f32_e32 v232, v24
	v_exp_f32_e32 v234, v25
	v_exp_f32_e32 v230, v26
	v_exp_f32_e32 v233, v27
	v_exp_f32_e32 v228, v28
	v_exp_f32_e32 v231, v29
	v_exp_f32_e32 v227, v30
	v_exp_f32_e32 v229, v31
	s_or_b32 s48, s63, s80
	s_mov_b32 s49, s64
	v_lshl_add_u64 v[178:179], s[48:49], 0, v[34:35]
	s_or_b32 s48, s59, s79
	s_mov_b32 s49, s60
	v_lshl_add_u64 v[180:181], s[48:49], 0, v[38:39]
	v_lshl_add_u64 v[182:183], s[48:49], 0, v[36:37]
	v_lshl_add_u64 v[184:185], s[48:49], 0, v[176:177]
	v_lshl_add_u64 v[186:187], s[48:49], 0, v[32:33]
	s_mov_b32 s54, 0x14000
	s_mov_b32 s48, -1
	s_mov_b32 s49, 0xa000
	v_mov_b32_e32 v176, 0
	v_mov_b32_e32 v16, 0
	v_mov_b32_e32 v17, v177
	v_mov_b32_e32 v18, v177
	v_mov_b32_e32 v19, v177
	v_mov_b32_e32 v20, v177
	v_mov_b32_e32 v21, v177
	v_mov_b32_e32 v22, v177
	v_mov_b32_e32 v23, v177
	v_mov_b32_e32 v24, v177
	v_mov_b32_e32 v25, v177
	v_mov_b32_e32 v26, v177
	v_mov_b32_e32 v27, v177
	v_mov_b32_e32 v28, v177
	v_mov_b32_e32 v29, v177
	v_mov_b32_e32 v30, v177
	v_mov_b32_e32 v31, v177
	v_mov_b32_e32 v32, 0
	v_mov_b32_e32 v34, v177
	v_mov_b32_e32 v36, v177
	v_mov_b32_e32 v38, v177
	v_mov_b32_e32 v40, v177
	v_mov_b32_e32 v41, v177
	v_mov_b32_e32 v42, v177
	v_mov_b32_e32 v43, v177
	v_mov_b32_e32 v44, v177
	v_mov_b32_e32 v45, v177
	v_mov_b32_e32 v46, v177
	v_mov_b32_e32 v47, v177
	v_mov_b32_e32 v48, 0
	v_mov_b32_e32 v49, v177
	v_mov_b32_e32 v50, v177
	v_mov_b32_e32 v51, v177
	v_mov_b32_e32 v52, v177
	v_mov_b32_e32 v53, v177
	v_mov_b32_e32 v54, v177
	v_mov_b32_e32 v55, v177
	v_mov_b32_e32 v56, v177
	v_mov_b32_e32 v57, v177
	v_mov_b32_e32 v58, v177
	v_mov_b32_e32 v59, v177
	v_mov_b32_e32 v60, v177
	v_mov_b32_e32 v61, v177
	v_mov_b32_e32 v62, v177
	v_mov_b32_e32 v63, v177
	v_mov_b32_e32 v64, 0
	v_mov_b32_e32 v65, v177
	v_mov_b32_e32 v66, v177
	v_mov_b32_e32 v67, v177
	v_mov_b32_e32 v68, v177
	v_mov_b32_e32 v69, v177
	v_mov_b32_e32 v70, v177
	v_mov_b32_e32 v71, v177
	v_mov_b32_e32 v72, v177
	v_mov_b32_e32 v73, v177
	v_mov_b32_e32 v74, v177
	v_mov_b32_e32 v75, v177
	v_mov_b32_e32 v76, v177
	v_mov_b32_e32 v77, v177
	v_mov_b32_e32 v78, v177
	v_mov_b32_e32 v79, v177
